# XCD-owned row tiles for out-proj/ff1/ff2 (XCD x owns row tiles 6x..6x+5) and XCD-local grid barriers (no L2 writeback, no cross-XCD round) after out-proj and after ff1; runtime check of id%8==XCC with
# baseline (speedup 1.0000x reference)
_Z14fwd_megakernel4Args:
	s_mov_b64 s[80:81], s[0:1]
	s_load_dwordx4 s[16:19], s[0:1], 0x0
	s_load_dwordx2 s[4:5], s[0:1], 0x10
	s_nop 0
	s_load_dwordx2 s[0:1], s[0:1], 0x68
	s_nop 0
	s_load_dwordx8 s[8:15], s[80:81], 0x48
	s_load_dwordx8 s[36:43], s[80:81], 0xf0
	s_load_dwordx8 s[20:27], s[80:81], 0xd0
	s_load_dword s44, s[80:81], 0x110
	v_and_b32_e32 v1, 0x3ff, v0
	v_mbcnt_lo_u32_b32 v2, -1, 0
	s_waitcnt lgkmcnt(0)
	v_writelane_b32 v254, s0, 0
	v_readfirstlane_b32 s33, v1
	v_mbcnt_hi_u32_b32 v45, -1, v2
	v_writelane_b32 v254, s1, 1
	v_writelane_b32 v254, s20, 2
	s_add_u32 s0, s80, 0x108
	s_addc_u32 s1, s81, 0
	v_writelane_b32 v254, s21, 3
	v_writelane_b32 v254, s22, 4
	v_writelane_b32 v254, s23, 5
	v_writelane_b32 v254, s24, 6
	v_writelane_b32 v254, s25, 7
	v_writelane_b32 v254, s26, 8
	v_writelane_b32 v254, s27, 9
	s_and_b32 s20, s33, 0xffffffc0
	v_add_u32_e32 v228, s20, v45
	v_cmp_gt_i32_e32 vcc, 64, v228
	s_and_saveexec_b64 s[6:7], vcc
	v_lshl_add_u32 v2, v228, 2, 0
	v_add_u32_e32 v2, 0x20000, v2
	v_mov_b32_e32 v3, 0
	ds_write_b32 v2, v3
	s_or_b64 exec, exec, s[6:7]
	s_add_u32 s6, s40, 0x4000
	s_addc_u32 s7, s41, 0
	s_waitcnt lgkmcnt(0)
	s_barrier
	v_writelane_b32 v254, s6, 10
	s_getreg_b32 s3, hwreg(HW_REG_XCC_ID, 0, 4)
	v_sub_u32_e32 v2, 0, v45
	v_writelane_b32 v254, s7, 11
	s_and_b32 s71, s3, 15
	v_cmp_eq_u32_e64 s[26:27], s20, v2
	s_and_saveexec_b64 s[6:7], s[26:27]
	s_cbranch_execz .LBB0_5
	s_mov_b64 s[20:21], exec
	v_mbcnt_lo_u32_b32 v2, s20, 0
	v_mbcnt_hi_u32_b32 v2, s21, v2
	v_cmp_eq_u32_e32 vcc, 0, v2
	s_and_b64 s[22:23], exec, vcc
	s_mov_b64 exec, s[22:23]
	s_cbranch_execz .LBB0_5
	s_bcnt1_i32_b64 s20, s[20:21]
	s_lshl_b32 s22, s71, 8
	v_mov_b32_e32 v3, s20
	v_readlane_b32 s20, v254, 10
	v_mov_b32_e32 v2, s22
	v_readlane_b32 s21, v254, 11
	s_nop 4
	global_atomic_add v2, v3, s[20:21] offset:1024
	s_and_b32 s22, s2, 7
	s_cmp_eq_u32 s22, s71
	s_cbranch_scc1 .Lmy_map_ok
	v_mov_b32_e32 v2, 0x3800
	s_nop 0
	global_atomic_add v2, v3, s[20:21]
.Lmy_map_ok:
.LBB0_5:
	s_or_b64 exec, exec, s[6:7]
	s_add_u32 s74, s40, 0x100000
	s_addc_u32 s75, s41, 0
	s_cmpk_gt_i32 s2, 0x17f
	s_cbranch_scc1 .LBB0_88
	s_cmp_lg_u64 s[12:13], 0
	s_movk_i32 s20, 0xf000
	s_cselect_b64 s[6:7], -1, 0
	s_movk_i32 s30, 0x3ff
	v_mov_b32_e32 v9, 0
	s_mov_b32 s21, -1
	s_movk_i32 s31, 0xfc00
	s_movk_i32 s34, 0x6000
	s_mov_b64 s[22:23], 0xc0000
	s_movk_i32 s35, 0x900
	s_movk_i32 s45, 0x240
	s_mov_b32 s46, s2
	s_branch .LBB0_8

.LBB0_452:
	v_writelane_b32 v254, s78, 13
	s_nop 1
	v_writelane_b32 v254, s79, 14
	v_writelane_b32 v254, s74, 15
	s_nop 1
	v_writelane_b32 v254, s75, 16
	s_or_b64 exec, exec, s[0:1]
	v_readlane_b32 s58, v254, 10
	v_readlane_b32 s59, v254, 11
	v_mov_b32_e32 v0, 0x3800
	s_nop 4
	global_load_dword v0, v0, s[58:59] sc1
	s_waitcnt vmcnt(0)
	v_readfirstlane_b32 s58, v0
	s_cmp_eq_u32 s58, 0
	s_cselect_b32 s58, 1, 0
	s_nop 0
	v_writelane_b32 v255, s58, 46
	s_ashr_i32 s43, s2, 31
	s_lshr_b32 s0, s43, 29
	s_add_i32 s0, s2, s0
	s_and_b32 s1, s0, -8
	s_sub_i32 s1, s2, s1
	s_add_i32 s4, s76, 0xfffffa00
	s_cmp_lt_i32 s1, 0
	s_movk_i32 s7, 0x61
	s_cselect_b32 s5, 45, 44
	s_cselect_b32 s6, 25, 24
	s_cselect_b32 s7, s7, 0x60
	s_cmpk_gt_i32 s42, 0xc0
	s_cselect_b32 s33, s4, s76
	s_add_i32 s4, s42, 0xffffff40
	s_cmpk_gt_i32 s42, 0xc0
	s_cselect_b32 s63, s4, s42
	s_add_i32 s4, s2, 0xffffff40
	s_mov_b32 s8, s76
	s_cmpk_gt_i32 s42, 0xc0
	v_writelane_b32 v254, s8, 17
	s_cselect_b32 s13, s4, s2
	s_cmpk_lt_i32 s2, 0x200
	v_writelane_b32 v254, s9, 18
	s_cselect_b64 s[8:9], -1, 0
	v_writelane_b32 v254, s8, 19
	s_add_i32 s4, s2, 0xa0
	s_bfe_u32 s4, s4, 0x50003
	v_writelane_b32 v254, s9, 20
	s_and_b32 s8, s2, 7
	s_mul_i32 s8, s8, 20
	s_add_i32 s4, s4, s8
	s_mul_i32 s8, s4, 0xcd
	s_bfe_u32 s8, s8, 0x3000d
	s_mul_i32 s9, s8, 40
	s_mul_i32 s5, s5, s1
	s_sub_i32 s9, s4, s9
	s_ashr_i32 s4, s0, 3
	s_add_i32 s5, s5, s4
	s_mul_hi_i32 s0, s5, 0x2e8ba2e9
	s_lshr_b32 s11, s0, 31
	s_ashr_i32 s0, s0, 4
	s_add_i32 s0, s0, s11
	s_mul_i32 s11, s0, 0x58
	s_sub_i32 s5, s5, s11
	s_bfe_i32 s11, s5, 0x80000
	s_bfe_u32 s11, s11, 0x3000c
	s_add_i32 s11, s5, s11
	s_bfe_i32 s12, s11, 0x80000
	s_and_b32 s11, s11, 0xf8
	s_lshl_b32 s8, s8, 2
	s_sub_i32 s5, s5, s11
	s_and_b32 s10, s8, 28
	s_lshl_b32 s0, s0, 3
	s_sext_i32_i8 s5, s5
	s_sub_i32 s10, 16, s10
	s_sext_i32_i16 s12, s12
	s_add_i32 s0, s0, s5
	s_min_u32 s10, s10, 4
	s_ashr_i32 s11, s12, 3
	s_add_i32 s0, s0, 16
	s_ashr_i32 s51, s42, 31
	s_add_u32 s48, s38, 0x4820000
	s_addc_u32 s49, s39, 0
	s_add_u32 s50, s38, 0x3820000
	s_addc_u32 s68, s39, 0
	s_add_u32 s69, s38, 0x5820000
	s_addc_u32 s62, s39, 0
	v_writelane_b32 v254, s11, 21
	s_add_u32 s14, s40, 0x4200
	v_writelane_b32 v254, s0, 22
	s_addc_u32 s15, s41, 0
	v_writelane_b32 v254, s14, 23
	s_waitcnt lgkmcnt(0)
	v_cvt_f32_ubyte0_e32 v0, s10
	v_rcp_iflag_f32_e32 v1, v0
	v_writelane_b32 v254, s15, 24
	s_add_u32 s14, s40, 0x7400
	s_addc_u32 s15, s41, 0
	v_writelane_b32 v254, s14, 25
	v_cvt_f32_ubyte0_e32 v2, s9
	v_mul_f32_e32 v1, v2, v1
	v_writelane_b32 v254, s15, 26
	s_add_u32 s14, s40, 0x7500
	s_addc_u32 s15, s41, 0
	v_writelane_b32 v254, s14, 27
	s_add_u32 s0, s40, 0x2000
	v_trunc_f32_e32 v1, v1
	v_writelane_b32 v254, s15, 28
	v_writelane_b32 v254, s0, 29
	s_addc_u32 s0, s41, 0
	s_cmpk_lt_i32 s2, 0xc0
	v_writelane_b32 v254, s0, 30
	s_cselect_b64 s[14:15], -1, 0
	v_writelane_b32 v254, s14, 31
	s_cmp_lt_i32 s13, 0
	v_cvt_u32_f32_e32 v3, v1
	v_writelane_b32 v254, s15, 32
	s_cselect_b64 s[14:15], -1, 0
	v_writelane_b32 v254, s14, 33
	s_cmpk_lt_u32 s13, 0x6c
	v_fma_f32 v1, -v1, v0, v2
	v_writelane_b32 v254, s15, 34
	s_cselect_b64 s[14:15], -1, 0
	v_writelane_b32 v254, s14, 35
	s_add_u32 s0, s40, 0x400000
	s_mov_b32 s97, 0
	v_writelane_b32 v254, s15, 36
	v_writelane_b32 v254, s0, 37
	s_addc_u32 s0, s41, 0
	v_writelane_b32 v254, s0, 38
	s_add_u32 s0, s40, 0x300000
	v_writelane_b32 v254, s0, 39
	s_addc_u32 s0, s41, 0
	s_cmpk_lt_i32 s2, 0x300
	v_writelane_b32 v254, s0, 40
	s_cselect_b64 s[14:15], -1, 0
	v_writelane_b32 v254, s14, 41
	s_lshl_b32 s0, s13, 3
	v_mov_b32_e32 v65, 0
	v_writelane_b32 v254, s15, 42
	v_writelane_b32 v254, s0, 43
	s_add_u32 s0, s40, 0x4600000
	v_writelane_b32 v254, s0, 44
	s_addc_u32 s0, s41, 0
	v_writelane_b32 v254, s0, 45
	s_add_u32 s0, s40, 0x2600000
	v_writelane_b32 v254, s0, 46
	s_addc_u32 s0, s41, 0
	v_writelane_b32 v254, s0, 47
	s_add_u32 s0, s40, 0x1e00000
	v_writelane_b32 v254, s0, 48
	s_addc_u32 s0, s41, 0
	v_writelane_b32 v254, s0, 49
	s_add_u32 s0, s40, 0x800000
	v_writelane_b32 v254, s0, 50
	s_addc_u32 s0, s41, 0
	v_writelane_b32 v254, s0, 51
	s_add_i32 s0, s2, 0xfffffe00
	s_cmp_gt_u32 s0, 0xffffff5f
	s_mul_i32 s0, s1, s6
	s_cselect_b64 s[14:15], -1, 0
	s_add_i32 s0, s0, s4
	s_ashr_i32 s5, s0, 31
	s_lshr_b32 s5, s5, 27
	s_add_i32 s5, s0, s5
	s_ashr_i32 s6, s5, 5
	s_and_b32 s5, s5, 0xffe0
	s_sub_i32 s5, s0, s5
	s_bfe_i32 s0, s5, 0x80000
	s_bfe_u32 s0, s0, 0x3000c
	s_add_i32 s11, s5, s0
	s_mul_i32 s1, s1, s7
	s_bfe_i32 s0, s11, 0x80000
	s_and_b32 s11, s11, 0xf8
	s_add_i32 s1, s1, s4
	s_sub_i32 s5, s5, s11
	s_ashr_i32 s4, s1, 31
	v_writelane_b32 v254, s14, 52
	s_lshl_b32 s6, s6, 3
	s_sext_i32_i16 s12, s0
	s_sext_i32_i8 s5, s5
	s_lshr_b32 s4, s4, 25
	v_writelane_b32 v254, s15, 53
	s_add_i32 s14, s6, s5
	s_ashr_i32 s5, s12, 3
	s_add_i32 s4, s1, s4
	v_writelane_b32 v254, s5, 54
	s_ashr_i32 s5, s4, 7
	s_and_b32 s4, s4, 0xff80
	s_sub_i32 s1, s1, s4
	s_bfe_i32 s4, s1, 0x80000
	s_bfe_u32 s4, s4, 0x3000c
	s_add_i32 s6, s1, s4
	s_bfe_i32 s4, s6, 0x80000
	s_and_b32 s6, s6, 0xf8
	s_sub_i32 s1, s1, s6
	s_lshl_b32 s5, s5, 3
	s_sext_i32_i16 s7, s4
	s_sext_i32_i8 s1, s1
	s_add_i32 s16, s5, s1
	s_ashr_i32 s1, s7, 3
	v_writelane_b32 v254, s1, 55
	s_mov_b32 s6, s16
	s_lshr_b32 s4, s7, 3
	s_ashr_i32 s17, s16, 31
	v_writelane_b32 v254, s6, 56
	s_bfe_i64 s[4:5], s[4:5], 0x100000
	s_lshl_b64 s[4:5], s[4:5], 19
	v_writelane_b32 v254, s7, 57
	s_lshl_b64 s[6:7], s[16:17], 19
	v_writelane_b32 v254, s6, 58
	s_ashr_i32 s15, s14, 31
	s_lshr_b32 s0, s12, 3
	v_writelane_b32 v254, s7, 59
	v_writelane_b32 v254, s4, 60
	s_bfe_i64 s[0:1], s[0:1], 0x100000
	v_mov_b32_e32 v229, 0x358637bd
	v_writelane_b32 v254, s5, 61
	s_lshl_b64 s[4:5], s[14:15], 19
	v_writelane_b32 v254, s4, 62
	v_mov_b32_e32 v230, 1
	v_mov_b32_e32 v190, 0x3f4ccccd
	v_writelane_b32 v254, s5, 63
	s_lshl_b64 s[4:5], s[0:1], 19
	v_writelane_b32 v255, s4, 0
	s_lshl_b64 s[0:1], s[0:1], 21
	v_mov_b32_e32 v231, 0x1000
	v_writelane_b32 v255, s5, 1
	s_mov_b32 s4, s14
	v_writelane_b32 v255, s4, 2
	v_mov_b32_e32 v232, 0x3ecc95a3
	v_mov_b32_e32 v233, 0x3c088889
	v_writelane_b32 v255, s5, 3
	s_lshl_b64 s[4:5], s[14:15], 21
	v_writelane_b32 v255, s4, 4
	v_mov_b32_e32 v234, 0x7f800000
	v_mov_b32_e32 v235, 0x7fc00000
	v_writelane_b32 v255, s5, 5
	v_writelane_b32 v255, s0, 6
	v_readfirstlane_b32 s4, v3
	v_mov_b32_e32 v236, 0xff800000
	v_writelane_b32 v255, s1, 7
	v_cmp_ge_f32_e64 s[0:1], |v1|, v0
	s_cmp_lg_u64 s[0:1], 0
	s_addc_u32 s0, s4, 0
	s_mul_i32 s1, s0, s10
	s_sub_i32 s1, s9, s1
	s_add_i32 s1, s1, s8
	s_and_b32 s1, s1, 0xff
	s_and_b32 s4, s0, 0xff
	s_cmp_gt_u32 s4, 7
	v_writelane_b32 v255, s1, 8
	s_cselect_b64 s[0:1], -1, 0
	s_cmp_lg_u64 s[0:1], 0
	s_addc_u32 s0, s4, 0
	s_load_dwordx8 s[4:11], s[80:81], 0xd0
	v_writelane_b32 v255, s0, 9
	v_writelane_b32 v255, s13, 10
	s_lshl_b32 s0, s13, 6
	v_writelane_b32 v255, s0, 11
	s_addk_i32 s0, 0xf500
	s_lshl_b32 s79, s63, 6
	s_waitcnt lgkmcnt(0)
	s_mov_b64 s[4:5], s[8:9]
	v_writelane_b32 v255, s0, 12
	s_add_u32 s0, s4, 0x1000000
	s_addc_u32 s1, s5, 0
	v_writelane_b32 v255, s0, 13
	v_mov_b32_e32 v237, 0x3e800000
	v_bfrev_b32_e32 v238, 0.5
	v_writelane_b32 v255, s1, 14
	s_load_dwordx2 s[0:1], s[80:81], 0x68
	v_mov_b64_e32 v[192:193], 0xc0
	v_mov_b64_e32 v[194:195], 0xbf
	v_not_b32_e32 v239, 30
	s_mov_b32 s55, 0x800000
	s_waitcnt lgkmcnt(0)
	s_add_u32 s0, s0, 0xb00000
	s_addc_u32 s1, s1, 0
	v_writelane_b32 v255, s0, 15
	s_movk_i32 s92, 0x3ff
	s_movk_i32 s93, 0x1600
	v_writelane_b32 v255, s1, 16
	s_add_i32 s0, 0, 0x20020
	v_writelane_b32 v255, s0, 17
	s_add_i32 s0, 0, 0x20024
	v_writelane_b32 v255, s0, 18
	s_add_i32 s0, 0, 0x12200
	v_writelane_b32 v255, s0, 19
	s_add_i32 s0, 0, 0x15800
	v_writelane_b32 v255, s0, 20
	s_brev_b32 s0, 1
	v_writelane_b32 v255, s0, 21
	s_movk_i32 s94, 0x90
	s_movk_i32 s95, 0xf7
	v_writelane_b32 v255, s1, 22
	v_writelane_b32 v255, s2, 23
	v_writelane_b32 v255, s3, 24
	v_writelane_b32 v255, s80, 25
	s_movk_i32 s46, 0x7d0
	s_add_i32 s47, 0, 0x20000
	v_writelane_b32 v255, s81, 26
	v_writelane_b32 v255, s63, 27
	v_writelane_b32 v255, s79, 28
	s_mov_b32 s52, 0x41000000
	s_movk_i32 s54, 0xfeff
	s_mov_b32 s64, 0xc800
	s_mov_b32 s65, 0xbe800000
	s_movk_i32 s78, 0x2c00
	s_mov_b64 s[28:29], 0
	s_mov_b64 s[30:31], 0x80
	s_mov_b64 s[72:73], 0
	s_mov_b32 s74, s97
	s_and_b32 s58, s2, 7
	s_lshr_b32 s59, s2, 3
	s_mul_i32 s60, s59, 43
	s_lshr_b32 s60, s60, 8
	s_mul_i32 s61, s60, 6
	s_sub_i32 s59, s59, s61
	s_mul_i32 s58, s58, 6
	s_add_i32 s58, s58, s59
	s_mov_b32 s61, 0
	v_writelane_b32 v254, s60, 54
	v_writelane_b32 v254, s60, 55
	v_writelane_b32 v254, s58, 56
	v_writelane_b32 v254, s61, 57
	v_writelane_b32 v255, s58, 2
	v_writelane_b32 v255, s61, 3
	v_writelane_b32 v254, s61, 59
	v_writelane_b32 v254, s61, 61
	v_writelane_b32 v254, s61, 63
	v_writelane_b32 v255, s61, 1
	v_writelane_b32 v255, s61, 5
	v_writelane_b32 v255, s61, 7
	s_lshl_b32 s59, s58, 19
	v_writelane_b32 v254, s59, 58
	v_writelane_b32 v254, s59, 62
	s_lshl_b32 s59, s58, 21
	v_writelane_b32 v255, s59, 4
	s_lshl_b32 s59, s60, 19
	v_writelane_b32 v254, s59, 60
	v_writelane_b32 v255, s59, 0
	s_lshl_b32 s59, s60, 21
	v_writelane_b32 v255, s59, 6
	v_writelane_b32 v255, s33, 29
	s_barrier
	s_mov_b64 s[6:7], s[10:11]
	s_branch .LBB0_455

.LBB0_2096:
	s_andn2_saveexec_b64 s[0:1], s[16:17]
	s_cbranch_execz .LBB0_2116
	v_readlane_b32 s0, v255, 46
	s_cmp_lg_u32 s0, 0
	s_cbranch_scc1 .Lmy_locbar_a
	s_mov_b64 s[16:17], exec
	buffer_wbl2 sc1
	s_waitcnt lgkmcnt(0)
	s_waitcnt vmcnt(0)
	v_mbcnt_lo_u32_b32 v1, s16, 0
	v_mbcnt_hi_u32_b32 v1, s17, v1
	v_cmp_eq_u32_e32 vcc, 0, v1
	s_and_saveexec_b64 s[18:19], vcc
	s_cbranch_execz .LBB0_2099
	s_bcnt1_i32_b64 s0, s[16:17]
	v_mov_b32_e32 v2, s0
	v_readlane_b32 s0, v254, 25
	v_readlane_b32 s1, v254, 26
	s_nop 4
	global_atomic_add v2, v65, v2, s[0:1] sc0

.Lmy_locbar_a:
	s_mov_b64 s[16:17], exec
	v_mbcnt_lo_u32_b32 v0, s16, 0
	v_mbcnt_hi_u32_b32 v0, s17, v0
	v_cmp_eq_u32_e32 vcc, 0, v0
	s_waitcnt vmcnt(0)
	s_and_saveexec_b64 s[18:19], vcc
	s_cbranch_execz .LBB0_2115
	s_add_i32 s96, s4, 0x900
	s_lshl_b64 s[0:1], s[96:97], 2
	v_readlane_b32 s4, v254, 10
	v_readlane_b32 s5, v254, 11
	s_add_u32 s0, s4, s0
	s_addc_u32 s1, s5, s1
	s_bcnt1_i32_b64 s4, s[16:17]
	v_mov_b32_e32 v0, s4
	global_atomic_add v65, v0, s[0:1]

.LBB0_2122:
	s_add_i32 s12, s12, 1
	s_mul_i32 s0, s12, s51
	s_mul_hi_u32 s1, s12, s42
	s_add_i32 s1, s1, s0
	s_mul_i32 s0, s12, s42
	s_add_u32 s66, s0, s2
	s_addc_u32 s67, s1, s43
	v_mov_b64_e32 v[0:1], 0x300
	v_cmp_lt_i64_e64 s[6:7], s[66:67], v[0:1]
	v_mov_b64_e32 v[0:1], 0x2ff
	v_cmp_gt_i64_e32 vcc, s[66:67], v[0:1]
	s_cbranch_vccnz .LBB0_2124
	s_and_b32 s0, s66, 7
	s_lshr_b32 s1, s66, 3
	s_mul_i32 s13, s1, 43
	s_lshr_b32 s80, s13, 8
	s_mul_i32 s13, s80, 6
	s_sub_i32 s1, s1, s13
	s_mul_i32 s0, s0, 6
	s_add_i32 s82, s0, s1

.LBB0_2149:
	s_andn2_saveexec_b64 s[0:1], s[18:19]
	s_cbranch_execz .LBB0_2169
	v_readlane_b32 s0, v255, 46
	s_cmp_lg_u32 s0, 0
	s_cbranch_scc1 .Lmy_locbar_b
	s_mov_b64 s[18:19], exec
	buffer_wbl2 sc1
	s_waitcnt lgkmcnt(0)
	s_waitcnt vmcnt(0)
	v_mbcnt_lo_u32_b32 v1, s18, 0
	v_mbcnt_hi_u32_b32 v1, s19, v1
	v_cmp_eq_u32_e32 vcc, 0, v1
	s_and_saveexec_b64 s[20:21], vcc
	s_cbranch_execz .LBB0_2152
	s_bcnt1_i32_b64 s0, s[18:19]
	v_mov_b32_e32 v2, s0
	v_readlane_b32 s0, v254, 25
	v_readlane_b32 s1, v254, 26
	s_nop 4
	global_atomic_add v2, v65, v2, s[0:1] sc0

.Lmy_locbar_b:
	s_mov_b64 s[18:19], exec
	v_mbcnt_lo_u32_b32 v0, s18, 0
	v_mbcnt_hi_u32_b32 v0, s19, v0
	v_cmp_eq_u32_e32 vcc, 0, v0
	s_waitcnt vmcnt(0)
	s_and_saveexec_b64 s[20:21], vcc
	s_cbranch_execz .LBB0_2168
	s_add_i32 s96, s4, 0x900
	s_lshl_b64 s[0:1], s[96:97], 2
	v_readlane_b32 s4, v254, 10
	v_readlane_b32 s5, v254, 11
	s_add_u32 s0, s4, s0
	s_addc_u32 s1, s5, s1
	s_bcnt1_i32_b64 s4, s[18:19]
	v_mov_b32_e32 v0, s4
	global_atomic_add v65, v0, s[0:1]
